# v17 + hand-written in-projection bias GEMV in the prologue (one load round for the LDS staging, weight rows prefetched, batched DPP/bpermute reductions)
# speedup vs baseline: 1.1661x; 1.0030x over previous
; #define GASP __attribute__((address_space(1)))
; #define LAS __attribute__((address_space(3)))
; __device__ __forceinline__ float bflo(unsigned w) { return __uint_as_float(w << 16); }
; __device__ __forceinline__ float bfhi(unsigned w) { return __uint_as_float(w & 0xffff0000u); }
; __global__ void __launch_bounds__(NWAVES * 64, 2) fwd_kernel(Args args) {
;     ...
;         LAS float* sh = (LAS float*)L;
;         for (int ll = 0; ll < DEPTH; ++ll) {
;             __syncthreads();
;             for (int i = tidp; i < 8 * 512; i += 512) { const int bb = i >> 9, k4 = (i & 511) * 4; *(LAS f32x4*)(sh + bb * 2048 + k4) = *(const GASP f32x4*)(modl + ((size_t)ll * 8 + bb) * 6144 + k4); }
;             __syncthreads();
;             const bf16* WT = WSP(const bf16, WS_WIN) + (size_t)ll * 6144 * 2048; float* bias = WSP(float, WS_BIAS) + (size_t)ll * 8 * 6144;
;             for (int r = gw; r < INW; r += NGW) {
;                 float a8[8];
; #pragma unroll
;                 for (int bb = 0; bb < 8; ++bb) a8[bb] = 0.f;
; #pragma unroll 1
;                 for (int j = 0; j < 4; ++j) { const int k = j * 512 + lane * 8; const v4u wv = *(const GASP v4u*)(WT + (size_t)r * 2048 + k);
;                     const float w0 = bflo(wv.x), w1 = bfhi(wv.x), w2 = bflo(wv.y), w3 = bfhi(wv.y), w4 = bflo(wv.z), w5 = bfhi(wv.z), w6 = bflo(wv.w), w7 = bfhi(wv.w);
; #pragma unroll
;                     for (int bb = 0; bb < 8; ++bb) { const f32x4 sa = *(const LAS f32x4*)(sh + bb * 2048 + k), sb = *(const LAS f32x4*)(sh + bb * 2048 + k + 4);
;                         a8[bb] += (sa.x * w0 + sa.y * w1) + (sa.z * w2 + sa.w * w3) + (sb.x * w4 + sb.y * w5) + (sb.z * w6 + sb.w * w7); } }
.LBB0_93:
	s_ashr_i32 s49, s48, 31
	v_lshl_add_u32 v144, s1, 6, v64
	v_lshlrev_b32_e32 v145, 4, v144
	v_lshlrev_b32_e32 v146, 5, v64
	v_lshlrev_b32_e32 v147, 4, v64
	v_xor_b32_e32 v149, 16, v64
	v_lshlrev_b32_e32 v149, 2, v149
	v_xor_b32_e32 v150, 32, v64
	v_lshlrev_b32_e32 v150, 2, v150
	s_mov_b32 s72, 0
	s_mov_b32 s88, 0xffff0000
	s_mov_b64 s[74:75], s[12:13]
	s_add_u32 s76, s12, 0x4a00000
	s_addc_u32 s77, s13, 0
	s_add_u32 s78, s12, 0x35a00000
	s_addc_u32 s79, s13, 0
.Lxs_bias_ll:
	s_barrier
	s_mov_b64 s[80:81], s[74:75]
	global_load_dwordx4 v[152:155], v145, s[80:81]
	s_add_u32 s80, s80, 0x6000
	s_addc_u32 s81, s81, 0
	global_load_dwordx4 v[156:159], v145, s[80:81]
	s_add_u32 s80, s80, 0x6000
	s_addc_u32 s81, s81, 0
	global_load_dwordx4 v[160:163], v145, s[80:81]
	s_add_u32 s80, s80, 0x6000
	s_addc_u32 s81, s81, 0
	global_load_dwordx4 v[164:167], v145, s[80:81]
	s_add_u32 s80, s80, 0x6000
	s_addc_u32 s81, s81, 0
	global_load_dwordx4 v[168:171], v145, s[80:81]
	s_add_u32 s80, s80, 0x6000
	s_addc_u32 s81, s81, 0
	global_load_dwordx4 v[172:175], v145, s[80:81]
	s_add_u32 s80, s80, 0x6000
	s_addc_u32 s81, s81, 0
	global_load_dwordx4 v[176:179], v145, s[80:81]
	s_add_u32 s80, s80, 0x6000
	s_addc_u32 s81, s81, 0
	global_load_dwordx4 v[180:183], v145, s[80:81]
	s_add_u32 s80, s80, 0x6000
	s_addc_u32 s81, s81, 0
	s_waitcnt vmcnt(0)
	ds_write_b128 v145, v[152:155] offset:0
	ds_write_b128 v145, v[156:159] offset:8192
	ds_write_b128 v145, v[160:163] offset:16384
	ds_write_b128 v145, v[164:167] offset:24576
	ds_write_b128 v145, v[168:171] offset:32768
	ds_write_b128 v145, v[172:175] offset:40960
	ds_write_b128 v145, v[176:179] offset:49152
	ds_write_b128 v145, v[180:183] offset:57344
	s_waitcnt lgkmcnt(0)
	s_barrier
	s_mov_b32 s82, s0
	s_cmp_lt_u32 s82, 0x1800
	s_cbranch_scc0 .Lxs_bias_next
	s_mov_b32 s83, s82
	s_lshl_b32 s84, s83, 12
	s_add_u32 s86, s76, s84
	s_addc_u32 s87, s77, 0
	global_load_dwordx4 v[184:187], v147, s[86:87] offset:0
	global_load_dwordx4 v[188:191], v147, s[86:87] offset:1024
	global_load_dwordx4 v[192:195], v147, s[86:87] offset:2048
	global_load_dwordx4 v[196:199], v147, s[86:87] offset:3072
.Lxs_bias_row:
	s_waitcnt vmcnt(0)
	v_mov_b32_e32 v200, v184
	v_mov_b32_e32 v201, v185
	v_mov_b32_e32 v202, v186
	v_mov_b32_e32 v203, v187
	v_mov_b32_e32 v204, v188
	v_mov_b32_e32 v205, v189
	v_mov_b32_e32 v206, v190
	v_mov_b32_e32 v207, v191
	v_mov_b32_e32 v208, v192
	v_mov_b32_e32 v209, v193
	v_mov_b32_e32 v210, v194
	v_mov_b32_e32 v211, v195
	v_mov_b32_e32 v212, v196
	v_mov_b32_e32 v213, v197
	v_mov_b32_e32 v214, v198
	v_mov_b32_e32 v215, v199
	s_add_i32 s83, s82, s48
	s_cmp_lt_u32 s83, 0x1800
	s_cbranch_scc0 .Lxs_bias_nopf
	s_lshl_b32 s84, s83, 12
	s_add_u32 s86, s76, s84
	s_addc_u32 s87, s77, 0
	global_load_dwordx4 v[184:187], v147, s[86:87] offset:0
	global_load_dwordx4 v[188:191], v147, s[86:87] offset:1024
	global_load_dwordx4 v[192:195], v147, s[86:87] offset:2048
	global_load_dwordx4 v[196:199], v147, s[86:87] offset:3072
.Lxs_bias_nopf:
	v_mov_b32_e32 v216, 0
	v_mov_b32_e32 v217, 0
	v_mov_b32_e32 v218, 0
	v_mov_b32_e32 v219, 0
	v_mov_b32_e32 v220, 0
	v_mov_b32_e32 v221, 0
	v_mov_b32_e32 v222, 0
	v_mov_b32_e32 v223, 0
	v_lshlrev_b32_e32 v224, 16, v200
	v_and_b32_e32 v225, s88, v200
	v_lshlrev_b32_e32 v226, 16, v201
	v_and_b32_e32 v227, s88, v201
	v_lshlrev_b32_e32 v228, 16, v202
	v_and_b32_e32 v229, s88, v202
	v_lshlrev_b32_e32 v230, 16, v203
	v_and_b32_e32 v231, s88, v203
	ds_read_b128 v[152:155], v146 offset:0
	ds_read_b128 v[156:159], v146 offset:16
	ds_read_b128 v[160:163], v146 offset:8192
	ds_read_b128 v[164:167], v146 offset:8208
	ds_read_b128 v[168:171], v146 offset:16384
	ds_read_b128 v[172:175], v146 offset:16400
	ds_read_b128 v[176:179], v146 offset:24576
	ds_read_b128 v[180:183], v146 offset:24592
	s_waitcnt lgkmcnt(0)
	v_fmac_f32_e32 v216, v152, v224
	v_fmac_f32_e32 v217, v160, v224
	v_fmac_f32_e32 v218, v168, v224
	v_fmac_f32_e32 v219, v176, v224
	v_fmac_f32_e32 v216, v153, v225
	v_fmac_f32_e32 v217, v161, v225
	v_fmac_f32_e32 v218, v169, v225
	v_fmac_f32_e32 v219, v177, v225
	v_fmac_f32_e32 v216, v154, v226
	v_fmac_f32_e32 v217, v162, v226
	v_fmac_f32_e32 v218, v170, v226
	v_fmac_f32_e32 v219, v178, v226
	v_fmac_f32_e32 v216, v155, v227
	v_fmac_f32_e32 v217, v163, v227
	v_fmac_f32_e32 v218, v171, v227
	v_fmac_f32_e32 v219, v179, v227
	v_fmac_f32_e32 v216, v156, v228
	v_fmac_f32_e32 v217, v164, v228
	v_fmac_f32_e32 v218, v172, v228
	v_fmac_f32_e32 v219, v180, v228
	v_fmac_f32_e32 v216, v157, v229
	v_fmac_f32_e32 v217, v165, v229
	v_fmac_f32_e32 v218, v173, v229
	v_fmac_f32_e32 v219, v181, v229
	v_fmac_f32_e32 v216, v158, v230
	v_fmac_f32_e32 v217, v166, v230
	v_fmac_f32_e32 v218, v174, v230
	v_fmac_f32_e32 v219, v182, v230
	v_fmac_f32_e32 v216, v159, v231
	v_fmac_f32_e32 v217, v167, v231
	v_fmac_f32_e32 v218, v175, v231
	v_fmac_f32_e32 v219, v183, v231
	ds_read_b128 v[152:155], v146 offset:32768
	ds_read_b128 v[156:159], v146 offset:32784
	ds_read_b128 v[160:163], v146 offset:40960
	ds_read_b128 v[164:167], v146 offset:40976
	ds_read_b128 v[168:171], v146 offset:49152
	ds_read_b128 v[172:175], v146 offset:49168
	ds_read_b128 v[176:179], v146 offset:57344
	ds_read_b128 v[180:183], v146 offset:57360
	s_waitcnt lgkmcnt(0)
; #define GASP __attribute__((address_space(1)))
; #define LAS __attribute__((address_space(3)))
; __device__ __forceinline__ float bflo(unsigned w) { return __uint_as_float(w << 16); }
; __device__ __forceinline__ float bfhi(unsigned w) { return __uint_as_float(w & 0xffff0000u); }
; __global__ void __launch_bounds__(NWAVES * 64, 2) fwd_kernel(Args args) {
;     ...
;                 for (int j = 0; j < 4; ++j) { const int k = j * 512 + lane * 8; const v4u wv = *(const GASP v4u*)(WT + (size_t)r * 2048 + k);
;                     const float w0 = bflo(wv.x), w1 = bfhi(wv.x), w2 = bflo(wv.y), w3 = bfhi(wv.y), w4 = bflo(wv.z), w5 = bfhi(wv.z), w6 = bflo(wv.w), w7 = bfhi(wv.w);
; #pragma unroll
;                     for (int bb = 0; bb < 8; ++bb) { const f32x4 sa = *(const LAS f32x4*)(sh + bb * 2048 + k), sb = *(const LAS f32x4*)(sh + bb * 2048 + k + 4);
;                         a8[bb] += (sa.x * w0 + sa.y * w1) + (sa.z * w2 + sa.w * w3) + (sb.x * w4 + sb.y * w5) + (sb.z * w6 + sb.w * w7); } }
	v_fmac_f32_e32 v220, v152, v224
	v_fmac_f32_e32 v221, v160, v224
	v_fmac_f32_e32 v222, v168, v224
	v_fmac_f32_e32 v223, v176, v224
	v_fmac_f32_e32 v220, v153, v225
	v_fmac_f32_e32 v221, v161, v225
	v_fmac_f32_e32 v222, v169, v225
	v_fmac_f32_e32 v223, v177, v225
	v_fmac_f32_e32 v220, v154, v226
	v_fmac_f32_e32 v221, v162, v226
	v_fmac_f32_e32 v222, v170, v226
	v_fmac_f32_e32 v223, v178, v226
	v_fmac_f32_e32 v220, v155, v227
	v_fmac_f32_e32 v221, v163, v227
	v_fmac_f32_e32 v222, v171, v227
	v_fmac_f32_e32 v223, v179, v227
	v_fmac_f32_e32 v220, v156, v228
	v_fmac_f32_e32 v221, v164, v228
	v_fmac_f32_e32 v222, v172, v228
	v_fmac_f32_e32 v223, v180, v228
	v_fmac_f32_e32 v220, v157, v229
	v_fmac_f32_e32 v221, v165, v229
	v_fmac_f32_e32 v222, v173, v229
	v_fmac_f32_e32 v223, v181, v229
	v_fmac_f32_e32 v220, v158, v230
	v_fmac_f32_e32 v221, v166, v230
	v_fmac_f32_e32 v222, v174, v230
	v_fmac_f32_e32 v223, v182, v230
	v_fmac_f32_e32 v220, v159, v231
	v_fmac_f32_e32 v221, v167, v231
	v_fmac_f32_e32 v222, v175, v231
	v_fmac_f32_e32 v223, v183, v231
	v_lshlrev_b32_e32 v224, 16, v204
	v_and_b32_e32 v225, s88, v204
	v_lshlrev_b32_e32 v226, 16, v205
	v_and_b32_e32 v227, s88, v205
	v_lshlrev_b32_e32 v228, 16, v206
	v_and_b32_e32 v229, s88, v206
	v_lshlrev_b32_e32 v230, 16, v207
	v_and_b32_e32 v231, s88, v207
	ds_read_b128 v[152:155], v146 offset:2048
	ds_read_b128 v[156:159], v146 offset:2064
	ds_read_b128 v[160:163], v146 offset:10240
	ds_read_b128 v[164:167], v146 offset:10256
	ds_read_b128 v[168:171], v146 offset:18432
	ds_read_b128 v[172:175], v146 offset:18448
	ds_read_b128 v[176:179], v146 offset:26624
	ds_read_b128 v[180:183], v146 offset:26640
	s_waitcnt lgkmcnt(0)
	v_fmac_f32_e32 v216, v152, v224
	v_fmac_f32_e32 v217, v160, v224
	v_fmac_f32_e32 v218, v168, v224
	v_fmac_f32_e32 v219, v176, v224
	v_fmac_f32_e32 v216, v153, v225
	v_fmac_f32_e32 v217, v161, v225
	v_fmac_f32_e32 v218, v169, v225
	v_fmac_f32_e32 v219, v177, v225
	v_fmac_f32_e32 v216, v154, v226
	v_fmac_f32_e32 v217, v162, v226
	v_fmac_f32_e32 v218, v170, v226
	v_fmac_f32_e32 v219, v178, v226
	v_fmac_f32_e32 v216, v155, v227
	v_fmac_f32_e32 v217, v163, v227
	v_fmac_f32_e32 v218, v171, v227
	v_fmac_f32_e32 v219, v179, v227
	v_fmac_f32_e32 v216, v156, v228
	v_fmac_f32_e32 v217, v164, v228
	v_fmac_f32_e32 v218, v172, v228
	v_fmac_f32_e32 v219, v180, v228
	v_fmac_f32_e32 v216, v157, v229
	v_fmac_f32_e32 v217, v165, v229
	v_fmac_f32_e32 v218, v173, v229
	v_fmac_f32_e32 v219, v181, v229
	v_fmac_f32_e32 v216, v158, v230
	v_fmac_f32_e32 v217, v166, v230
	v_fmac_f32_e32 v218, v174, v230
	v_fmac_f32_e32 v219, v182, v230
	v_fmac_f32_e32 v216, v159, v231
	v_fmac_f32_e32 v217, v167, v231
	v_fmac_f32_e32 v218, v175, v231
	v_fmac_f32_e32 v219, v183, v231
	ds_read_b128 v[152:155], v146 offset:34816
	ds_read_b128 v[156:159], v146 offset:34832
	ds_read_b128 v[160:163], v146 offset:43008
	ds_read_b128 v[164:167], v146 offset:43024
	ds_read_b128 v[168:171], v146 offset:51200
	ds_read_b128 v[172:175], v146 offset:51216
	ds_read_b128 v[176:179], v146 offset:59392
	ds_read_b128 v[180:183], v146 offset:59408
	s_waitcnt lgkmcnt(0)
	v_fmac_f32_e32 v220, v152, v224
	v_fmac_f32_e32 v221, v160, v224
	v_fmac_f32_e32 v222, v168, v224
	v_fmac_f32_e32 v223, v176, v224
	v_fmac_f32_e32 v220, v153, v225
	v_fmac_f32_e32 v221, v161, v225
	v_fmac_f32_e32 v222, v169, v225
	v_fmac_f32_e32 v223, v177, v225
	v_fmac_f32_e32 v220, v154, v226
	v_fmac_f32_e32 v221, v162, v226
	v_fmac_f32_e32 v222, v170, v226
	v_fmac_f32_e32 v223, v178, v226
	v_fmac_f32_e32 v220, v155, v227
	v_fmac_f32_e32 v221, v163, v227
	v_fmac_f32_e32 v222, v171, v227
	v_fmac_f32_e32 v223, v179, v227
	v_fmac_f32_e32 v220, v156, v228
	v_fmac_f32_e32 v221, v164, v228
	v_fmac_f32_e32 v222, v172, v228
	v_fmac_f32_e32 v223, v180, v228
	v_fmac_f32_e32 v220, v157, v229
	v_fmac_f32_e32 v221, v165, v229
	v_fmac_f32_e32 v222, v173, v229
	v_fmac_f32_e32 v223, v181, v229
	v_fmac_f32_e32 v220, v158, v230
	v_fmac_f32_e32 v221, v166, v230
	v_fmac_f32_e32 v222, v174, v230
	v_fmac_f32_e32 v223, v182, v230
	v_fmac_f32_e32 v220, v159, v231
	v_fmac_f32_e32 v221, v167, v231
	v_fmac_f32_e32 v222, v175, v231
	v_fmac_f32_e32 v223, v183, v231
	v_lshlrev_b32_e32 v224, 16, v208
	v_and_b32_e32 v225, s88, v208
	v_lshlrev_b32_e32 v226, 16, v209
	v_and_b32_e32 v227, s88, v209
	v_lshlrev_b32_e32 v228, 16, v210
	v_and_b32_e32 v229, s88, v210
	v_lshlrev_b32_e32 v230, 16, v211
	v_and_b32_e32 v231, s88, v211
	ds_read_b128 v[152:155], v146 offset:4096
	ds_read_b128 v[156:159], v146 offset:4112
	ds_read_b128 v[160:163], v146 offset:12288
	ds_read_b128 v[164:167], v146 offset:12304
	ds_read_b128 v[168:171], v146 offset:20480
	ds_read_b128 v[172:175], v146 offset:20496
	ds_read_b128 v[176:179], v146 offset:28672
	ds_read_b128 v[180:183], v146 offset:28688
	s_waitcnt lgkmcnt(0)
	v_fmac_f32_e32 v216, v152, v224
	v_fmac_f32_e32 v217, v160, v224
	v_fmac_f32_e32 v218, v168, v224
	v_fmac_f32_e32 v219, v176, v224
	v_fmac_f32_e32 v216, v153, v225
	v_fmac_f32_e32 v217, v161, v225
	v_fmac_f32_e32 v218, v169, v225
	v_fmac_f32_e32 v219, v177, v225
	v_fmac_f32_e32 v216, v154, v226
	v_fmac_f32_e32 v217, v162, v226
	v_fmac_f32_e32 v218, v170, v226
	v_fmac_f32_e32 v219, v178, v226
	v_fmac_f32_e32 v216, v155, v227
	v_fmac_f32_e32 v217, v163, v227
	v_fmac_f32_e32 v218, v171, v227
	v_fmac_f32_e32 v219, v179, v227
	v_fmac_f32_e32 v216, v156, v228
	v_fmac_f32_e32 v217, v164, v228
	v_fmac_f32_e32 v218, v172, v228
	v_fmac_f32_e32 v219, v180, v228
	v_fmac_f32_e32 v216, v157, v229
	v_fmac_f32_e32 v217, v165, v229
	v_fmac_f32_e32 v218, v173, v229
	v_fmac_f32_e32 v219, v181, v229
	v_fmac_f32_e32 v216, v158, v230
	v_fmac_f32_e32 v217, v166, v230
	v_fmac_f32_e32 v218, v174, v230
	v_fmac_f32_e32 v219, v182, v230
	v_fmac_f32_e32 v216, v159, v231
	v_fmac_f32_e32 v217, v167, v231
	v_fmac_f32_e32 v218, v175, v231
	v_fmac_f32_e32 v219, v183, v231
	ds_read_b128 v[152:155], v146 offset:36864
	ds_read_b128 v[156:159], v146 offset:36880
	ds_read_b128 v[160:163], v146 offset:45056
	ds_read_b128 v[164:167], v146 offset:45072
	ds_read_b128 v[168:171], v146 offset:53248
	ds_read_b128 v[172:175], v146 offset:53264
	ds_read_b128 v[176:179], v146 offset:61440
	ds_read_b128 v[180:183], v146 offset:61456
	s_waitcnt lgkmcnt(0)
; #define GASP __attribute__((address_space(1)))
; #define LAS __attribute__((address_space(3)))
; __device__ __forceinline__ float bflo(unsigned w) { return __uint_as_float(w << 16); }
; __device__ __forceinline__ float bfhi(unsigned w) { return __uint_as_float(w & 0xffff0000u); }
; __global__ void __launch_bounds__(NWAVES * 64, 2) fwd_kernel(Args args) {
;     ...
;                 for (int j = 0; j < 4; ++j) { const int k = j * 512 + lane * 8; const v4u wv = *(const GASP v4u*)(WT + (size_t)r * 2048 + k);
;                     const float w0 = bflo(wv.x), w1 = bfhi(wv.x), w2 = bflo(wv.y), w3 = bfhi(wv.y), w4 = bflo(wv.z), w5 = bfhi(wv.z), w6 = bflo(wv.w), w7 = bfhi(wv.w);
; #pragma unroll
;                     for (int bb = 0; bb < 8; ++bb) { const f32x4 sa = *(const LAS f32x4*)(sh + bb * 2048 + k), sb = *(const LAS f32x4*)(sh + bb * 2048 + k + 4);
;                         a8[bb] += (sa.x * w0 + sa.y * w1) + (sa.z * w2 + sa.w * w3) + (sb.x * w4 + sb.y * w5) + (sb.z * w6 + sb.w * w7); } }
	v_fmac_f32_e32 v220, v152, v224
	v_fmac_f32_e32 v221, v160, v224
	v_fmac_f32_e32 v222, v168, v224
	v_fmac_f32_e32 v223, v176, v224
	v_fmac_f32_e32 v220, v153, v225
	v_fmac_f32_e32 v221, v161, v225
	v_fmac_f32_e32 v222, v169, v225
	v_fmac_f32_e32 v223, v177, v225
	v_fmac_f32_e32 v220, v154, v226
	v_fmac_f32_e32 v221, v162, v226
	v_fmac_f32_e32 v222, v170, v226
	v_fmac_f32_e32 v223, v178, v226
	v_fmac_f32_e32 v220, v155, v227
	v_fmac_f32_e32 v221, v163, v227
	v_fmac_f32_e32 v222, v171, v227
	v_fmac_f32_e32 v223, v179, v227
	v_fmac_f32_e32 v220, v156, v228
	v_fmac_f32_e32 v221, v164, v228
	v_fmac_f32_e32 v222, v172, v228
	v_fmac_f32_e32 v223, v180, v228
	v_fmac_f32_e32 v220, v157, v229
	v_fmac_f32_e32 v221, v165, v229
	v_fmac_f32_e32 v222, v173, v229
	v_fmac_f32_e32 v223, v181, v229
	v_fmac_f32_e32 v220, v158, v230
	v_fmac_f32_e32 v221, v166, v230
	v_fmac_f32_e32 v222, v174, v230
	v_fmac_f32_e32 v223, v182, v230
	v_fmac_f32_e32 v220, v159, v231
	v_fmac_f32_e32 v221, v167, v231
	v_fmac_f32_e32 v222, v175, v231
	v_fmac_f32_e32 v223, v183, v231
	v_lshlrev_b32_e32 v224, 16, v212
	v_and_b32_e32 v225, s88, v212
	v_lshlrev_b32_e32 v226, 16, v213
	v_and_b32_e32 v227, s88, v213
	v_lshlrev_b32_e32 v228, 16, v214
	v_and_b32_e32 v229, s88, v214
	v_lshlrev_b32_e32 v230, 16, v215
	v_and_b32_e32 v231, s88, v215
	ds_read_b128 v[152:155], v146 offset:6144
	ds_read_b128 v[156:159], v146 offset:6160
	ds_read_b128 v[160:163], v146 offset:14336
	ds_read_b128 v[164:167], v146 offset:14352
	ds_read_b128 v[168:171], v146 offset:22528
	ds_read_b128 v[172:175], v146 offset:22544
	ds_read_b128 v[176:179], v146 offset:30720
	ds_read_b128 v[180:183], v146 offset:30736
	s_waitcnt lgkmcnt(0)
	v_fmac_f32_e32 v216, v152, v224
	v_fmac_f32_e32 v217, v160, v224
	v_fmac_f32_e32 v218, v168, v224
	v_fmac_f32_e32 v219, v176, v224
	v_fmac_f32_e32 v216, v153, v225
	v_fmac_f32_e32 v217, v161, v225
	v_fmac_f32_e32 v218, v169, v225
	v_fmac_f32_e32 v219, v177, v225
	v_fmac_f32_e32 v216, v154, v226
	v_fmac_f32_e32 v217, v162, v226
	v_fmac_f32_e32 v218, v170, v226
	v_fmac_f32_e32 v219, v178, v226
	v_fmac_f32_e32 v216, v155, v227
	v_fmac_f32_e32 v217, v163, v227
	v_fmac_f32_e32 v218, v171, v227
	v_fmac_f32_e32 v219, v179, v227
	v_fmac_f32_e32 v216, v156, v228
	v_fmac_f32_e32 v217, v164, v228
	v_fmac_f32_e32 v218, v172, v228
	v_fmac_f32_e32 v219, v180, v228
	v_fmac_f32_e32 v216, v157, v229
	v_fmac_f32_e32 v217, v165, v229
	v_fmac_f32_e32 v218, v173, v229
	v_fmac_f32_e32 v219, v181, v229
	v_fmac_f32_e32 v216, v158, v230
	v_fmac_f32_e32 v217, v166, v230
	v_fmac_f32_e32 v218, v174, v230
	v_fmac_f32_e32 v219, v182, v230
	v_fmac_f32_e32 v216, v159, v231
	v_fmac_f32_e32 v217, v167, v231
	v_fmac_f32_e32 v218, v175, v231
	v_fmac_f32_e32 v219, v183, v231
	ds_read_b128 v[152:155], v146 offset:38912
	ds_read_b128 v[156:159], v146 offset:38928
	ds_read_b128 v[160:163], v146 offset:47104
	ds_read_b128 v[164:167], v146 offset:47120
	ds_read_b128 v[168:171], v146 offset:55296
	ds_read_b128 v[172:175], v146 offset:55312
	ds_read_b128 v[176:179], v146 offset:63488
	ds_read_b128 v[180:183], v146 offset:63504
	s_waitcnt lgkmcnt(0)
; #define GASP __attribute__((address_space(1)))
; __global__ void __launch_bounds__(NWAVES * 64, 2) fwd_kernel(Args args) {
;     ...
;         for (int ll = 0; ll < DEPTH; ++ll) {
;     ...
;                         a8[bb] += (sa.x * w0 + sa.y * w1) + (sa.z * w2 + sa.w * w3) + (sb.x * w4 + sb.y * w5) + (sb.z * w6 + sb.w * w7); } }
; #pragma unroll
;                 for (int bb = 0; bb < 8; ++bb) { const float s = wave_sum(a8[bb], lane); if (lane == 0) ((GASP float*)bias)[(size_t)bb * 6144 + r] = s; }
;             }
;         }
	v_fmac_f32_e32 v220, v152, v224
	v_fmac_f32_e32 v221, v160, v224
	v_fmac_f32_e32 v222, v168, v224
	v_fmac_f32_e32 v223, v176, v224
	v_fmac_f32_e32 v220, v153, v225
	v_fmac_f32_e32 v221, v161, v225
	v_fmac_f32_e32 v222, v169, v225
	v_fmac_f32_e32 v223, v177, v225
	v_fmac_f32_e32 v220, v154, v226
	v_fmac_f32_e32 v221, v162, v226
	v_fmac_f32_e32 v222, v170, v226
	v_fmac_f32_e32 v223, v178, v226
	v_fmac_f32_e32 v220, v155, v227
	v_fmac_f32_e32 v221, v163, v227
	v_fmac_f32_e32 v222, v171, v227
	v_fmac_f32_e32 v223, v179, v227
	v_fmac_f32_e32 v220, v156, v228
	v_fmac_f32_e32 v221, v164, v228
	v_fmac_f32_e32 v222, v172, v228
	v_fmac_f32_e32 v223, v180, v228
	v_fmac_f32_e32 v220, v157, v229
	v_fmac_f32_e32 v221, v165, v229
	v_fmac_f32_e32 v222, v173, v229
	v_fmac_f32_e32 v223, v181, v229
	v_fmac_f32_e32 v220, v158, v230
	v_fmac_f32_e32 v221, v166, v230
	v_fmac_f32_e32 v222, v174, v230
	v_fmac_f32_e32 v223, v182, v230
	v_fmac_f32_e32 v220, v159, v231
	v_fmac_f32_e32 v221, v167, v231
	v_fmac_f32_e32 v222, v175, v231
	v_fmac_f32_e32 v223, v183, v231
	v_add_f32_dpp v216, v216, v216 quad_perm:[1,0,3,2] row_mask:0xf bank_mask:0xf
	v_add_f32_dpp v217, v217, v217 quad_perm:[1,0,3,2] row_mask:0xf bank_mask:0xf
	v_add_f32_dpp v218, v218, v218 quad_perm:[1,0,3,2] row_mask:0xf bank_mask:0xf
	v_add_f32_dpp v219, v219, v219 quad_perm:[1,0,3,2] row_mask:0xf bank_mask:0xf
	v_add_f32_dpp v220, v220, v220 quad_perm:[1,0,3,2] row_mask:0xf bank_mask:0xf
	v_add_f32_dpp v221, v221, v221 quad_perm:[1,0,3,2] row_mask:0xf bank_mask:0xf
	v_add_f32_dpp v222, v222, v222 quad_perm:[1,0,3,2] row_mask:0xf bank_mask:0xf
	v_add_f32_dpp v223, v223, v223 quad_perm:[1,0,3,2] row_mask:0xf bank_mask:0xf
	v_add_f32_dpp v216, v216, v216 quad_perm:[2,3,0,1] row_mask:0xf bank_mask:0xf
	v_add_f32_dpp v217, v217, v217 quad_perm:[2,3,0,1] row_mask:0xf bank_mask:0xf
	v_add_f32_dpp v218, v218, v218 quad_perm:[2,3,0,1] row_mask:0xf bank_mask:0xf
	v_add_f32_dpp v219, v219, v219 quad_perm:[2,3,0,1] row_mask:0xf bank_mask:0xf
	v_add_f32_dpp v220, v220, v220 quad_perm:[2,3,0,1] row_mask:0xf bank_mask:0xf
	v_add_f32_dpp v221, v221, v221 quad_perm:[2,3,0,1] row_mask:0xf bank_mask:0xf
	v_add_f32_dpp v222, v222, v222 quad_perm:[2,3,0,1] row_mask:0xf bank_mask:0xf
	v_add_f32_dpp v223, v223, v223 quad_perm:[2,3,0,1] row_mask:0xf bank_mask:0xf
	v_add_f32_dpp v216, v216, v216 row_ror:4 row_mask:0xf bank_mask:0xf
	v_add_f32_dpp v217, v217, v217 row_ror:4 row_mask:0xf bank_mask:0xf
	v_add_f32_dpp v218, v218, v218 row_ror:4 row_mask:0xf bank_mask:0xf
	v_add_f32_dpp v219, v219, v219 row_ror:4 row_mask:0xf bank_mask:0xf
	v_add_f32_dpp v220, v220, v220 row_ror:4 row_mask:0xf bank_mask:0xf
	v_add_f32_dpp v221, v221, v221 row_ror:4 row_mask:0xf bank_mask:0xf
	v_add_f32_dpp v222, v222, v222 row_ror:4 row_mask:0xf bank_mask:0xf
	v_add_f32_dpp v223, v223, v223 row_ror:4 row_mask:0xf bank_mask:0xf
	v_add_f32_dpp v216, v216, v216 row_ror:8 row_mask:0xf bank_mask:0xf
	v_add_f32_dpp v217, v217, v217 row_ror:8 row_mask:0xf bank_mask:0xf
	v_add_f32_dpp v218, v218, v218 row_ror:8 row_mask:0xf bank_mask:0xf
	v_add_f32_dpp v219, v219, v219 row_ror:8 row_mask:0xf bank_mask:0xf
	v_add_f32_dpp v220, v220, v220 row_ror:8 row_mask:0xf bank_mask:0xf
	v_add_f32_dpp v221, v221, v221 row_ror:8 row_mask:0xf bank_mask:0xf
	v_add_f32_dpp v222, v222, v222 row_ror:8 row_mask:0xf bank_mask:0xf
	v_add_f32_dpp v223, v223, v223 row_ror:8 row_mask:0xf bank_mask:0xf
	ds_bpermute_b32 v232, v149, v216
	ds_bpermute_b32 v233, v149, v217
	ds_bpermute_b32 v234, v149, v218
	ds_bpermute_b32 v235, v149, v219
	ds_bpermute_b32 v236, v149, v220
	ds_bpermute_b32 v237, v149, v221
	ds_bpermute_b32 v238, v149, v222
	ds_bpermute_b32 v239, v149, v223
	s_waitcnt lgkmcnt(0)
	v_add_f32_e32 v216, v216, v232
	v_add_f32_e32 v217, v217, v233
	v_add_f32_e32 v218, v218, v234
	v_add_f32_e32 v219, v219, v235
	v_add_f32_e32 v220, v220, v236
	v_add_f32_e32 v221, v221, v237
	v_add_f32_e32 v222, v222, v238
	v_add_f32_e32 v223, v223, v239
	ds_bpermute_b32 v232, v150, v216
	ds_bpermute_b32 v233, v150, v217
	ds_bpermute_b32 v234, v150, v218
	ds_bpermute_b32 v235, v150, v219
	ds_bpermute_b32 v236, v150, v220
	ds_bpermute_b32 v237, v150, v221
	ds_bpermute_b32 v238, v150, v222
	ds_bpermute_b32 v239, v150, v223
	s_waitcnt lgkmcnt(0)
	v_add_f32_e32 v216, v216, v232
	v_add_f32_e32 v217, v217, v233
	v_add_f32_e32 v218, v218, v234
	v_add_f32_e32 v219, v219, v235
	v_add_f32_e32 v220, v220, v236
	v_add_f32_e32 v221, v221, v237
	v_add_f32_e32 v222, v222, v238
	v_add_f32_e32 v223, v223, v239
	s_lshl_b32 s84, s82, 2
	v_mov_b32_e32 v148, s84
	s_mov_b64 s[90:91], s[78:79]
	s_mov_b64 s[92:93], exec
	s_mov_b64 exec, 1
	global_store_dword v148, v216, s[90:91]
	s_add_u32 s90, s90, 0x6000
	s_addc_u32 s91, s91, 0
	global_store_dword v148, v217, s[90:91]
	s_add_u32 s90, s90, 0x6000
	s_addc_u32 s91, s91, 0
	global_store_dword v148, v218, s[90:91]
	s_add_u32 s90, s90, 0x6000
	s_addc_u32 s91, s91, 0
	global_store_dword v148, v219, s[90:91]
	s_add_u32 s90, s90, 0x6000
	s_addc_u32 s91, s91, 0
	global_store_dword v148, v220, s[90:91]
	s_add_u32 s90, s90, 0x6000
	s_addc_u32 s91, s91, 0
	global_store_dword v148, v221, s[90:91]
	s_add_u32 s90, s90, 0x6000
	s_addc_u32 s91, s91, 0
	global_store_dword v148, v222, s[90:91]
	s_add_u32 s90, s90, 0x6000
	s_addc_u32 s91, s91, 0
	global_store_dword v148, v223, s[90:91]
	s_add_u32 s90, s90, 0x6000
	s_addc_u32 s91, s91, 0
	s_mov_b64 exec, s[92:93]
	s_mov_b32 s82, s83
	s_cmp_lt_u32 s82, 0x1800
	s_cbranch_scc1 .Lxs_bias_row
.Lxs_bias_next:
	s_add_i32 s72, s72, 1
	s_add_u32 s74, s74, 0x30000
	s_addc_u32 s75, s75, 0
	s_add_u32 s76, s76, 0x1800000
	s_addc_u32 s77, s77, 0
	s_add_u32 s78, s78, 0x30000
	s_addc_u32 s79, s79, 0
	s_cmp_lt_u32 s72, 4
	s_cbranch_scc1 .Lxs_bias_ll
